# static s_setprio 1 for waves 4-7 during the two attention phases (strategy: one static priority raise for the younger half)
# speedup vs baseline: 1.0163x; 1.0080x over previous
.LBB0_1092:
	s_or_b64 exec, exec, s[2:3]
	v_mov_b32_e32 v149, v196
	s_waitcnt lgkmcnt(0)
	s_barrier
	s_load_dwordx2 s[2:3], s[68:69], 0xb8
	v_readlane_b32 s1, v251, 26
	v_bfe_u32 v0, v149, 3, 1
	v_readfirstlane_b32 s0, v149
	v_lshl_add_u32 v3, v0, 2, s1
	s_movk_i32 s1, 0x3ff
	v_cmp_lt_i32_e32 vcc, s1, v149
	s_movk_i32 s1, 0x400
	v_cmp_gt_i32_e64 s[4:5], s1, v149
	s_ashr_i32 s0, s0, 6
	s_cmp_lt_u32 s0, 4
	s_cbranch_scc1 .Lprio_nsa
	s_setprio 1
.Lprio_nsa:
	s_waitcnt lgkmcnt(0)
	s_add_u32 s1, s2, 0x23b6e000
	v_writelane_b32 v250, s4, 12
	v_and_b32_e32 v214, 31, v149
	v_bfe_u32 v2, v149, 4, 2
	v_writelane_b32 v250, s5, 13
	v_writelane_b32 v250, s1, 14
	s_addc_u32 s1, s3, 0
	v_writelane_b32 v250, s1, 15
	s_add_u32 s1, s2, 0x23bae000
	v_writelane_b32 v250, s1, 16
	s_addc_u32 s1, s3, 0
	v_writelane_b32 v250, s1, 17
	v_cmp_eq_u32_e64 s[4:5], 0, v149
	v_and_b32_e32 v1, 63, v149
	v_and_b32_e32 v159, 7, v149
	v_writelane_b32 v250, s4, 18
	s_mov_b32 s1, 0
	v_cmp_eq_u32_e64 s[8:9], 0, v214
	v_writelane_b32 v250, s5, 19
	s_lshl_b32 s4, s0, 2
	v_writelane_b32 v250, s4, 20
	v_or_b32_e32 v213, s4, v0
	s_add_u32 s4, s2, 0x1a86c000
	v_writelane_b32 v250, s4, 21
	s_addc_u32 s4, s3, 0
	v_writelane_b32 v250, s4, 22
	s_add_u32 s4, s2, 0x2286e000
	s_addc_u32 s5, s3, 0
	v_writelane_b32 v250, s4, 23
	v_lshlrev_b32_e32 v0, 3, v2
	v_cmp_eq_u32_e64 s[10:11], 0, v1
	v_writelane_b32 v250, s5, 24
	s_add_u32 s4, s2, 0x23bee000
	s_addc_u32 s5, s3, 0
	v_writelane_b32 v250, s4, 25
	s_lshl_b32 s0, s0, 4
	v_lshlrev_b32_e32 v148, 2, v2
	v_writelane_b32 v250, s5, 26
	s_add_u32 s4, s2, 0x2186e000
	v_writelane_b32 v250, s4, 27
	s_addc_u32 s4, s3, 0
	v_writelane_b32 v250, s4, 28
	s_add_u32 s4, s2, 0x21c6e000
	v_writelane_b32 v250, s4, 29
	s_addc_u32 s4, s3, 0
	v_writelane_b32 v250, s4, 30
	s_add_u32 s4, s2, 0x2206e000
	v_writelane_b32 v250, s4, 31
	s_addc_u32 s4, s3, 0
	v_writelane_b32 v250, s4, 32
	s_add_u32 s4, s2, 0x2246e000
	v_writelane_b32 v250, s4, 33
	s_addc_u32 s4, s3, 0
	s_add_u32 s2, s2, 0x1f06c000
	v_writelane_b32 v250, s4, 34
	s_addc_u32 s3, s3, 0
	v_writelane_b32 v250, s2, 35
	v_cmp_lt_u32_e64 s[16:17], 3, v214
	v_cmp_lt_u32_e64 s[18:19], 4, v214
	v_writelane_b32 v250, s3, 36
	v_cmp_lt_u32_e64 s[2:3], 1, v214
	v_cmp_lt_u32_e64 s[20:21], 5, v214
	v_cmp_lt_u32_e64 s[22:23], 6, v214
	v_writelane_b32 v250, s2, 37
	v_cmp_lt_u32_e64 s[24:25], 7, v214
	v_cmp_lt_u32_e64 s[26:27], 8, v214
	v_writelane_b32 v250, s3, 38
	v_cmp_lt_u32_e64 s[2:3], 2, v214
	v_cmp_lt_u32_e64 s[28:29], 9, v214
	v_cmp_lt_u32_e64 s[30:31], 10, v214
	v_writelane_b32 v250, s2, 39
	v_cmp_lt_u32_e64 s[34:35], 11, v214
	v_cmp_lt_u32_e64 s[36:37], 12, v214
	v_writelane_b32 v250, s3, 40
	s_xor_b64 s[2:3], vcc, -1
	v_cmp_lt_u32_e64 s[38:39], 13, v214
	v_cmp_lt_u32_e64 s[40:41], 14, v214
	v_cmp_lt_u32_e64 s[42:43], 15, v214
	v_cmp_lt_u32_e64 s[44:45], 16, v214
	v_cmp_lt_u32_e64 s[46:47], 17, v214
	v_cmp_lt_u32_e64 s[48:49], 18, v214
	v_cmp_lt_u32_e64 s[50:51], 19, v214
	v_cmp_lt_u32_e64 s[52:53], 20, v214
	v_cmp_lt_u32_e64 s[54:55], 21, v214
	v_cmp_lt_u32_e64 s[56:57], 22, v214
	v_cmp_lt_u32_e64 s[58:59], 23, v214
	v_cmp_lt_u32_e64 s[60:61], 24, v214
	v_cmp_lt_u32_e64 s[62:63], 25, v214
	v_cmp_lt_u32_e64 s[64:65], 26, v214
	v_cmp_lt_u32_e64 s[66:67], 27, v214
	v_cmp_lt_u32_e64 s[68:69], 28, v214
	v_lshlrev_b32_e32 v215, 3, v149
	s_mov_b32 s4, -1
	v_writelane_b32 v250, s2, 41
	v_lshlrev_b32_e32 v150, 1, v0
	v_add_u32_e32 v216, s0, v3
	s_mov_b32 s6, 0
	v_cmp_lt_u32_e64 s[70:71], 29, v214
	v_cmp_eq_u32_e64 s[72:73], 31, v214
	v_writelane_b32 v250, s3, 42
	s_branch .LBB0_1096

.LBB0_1443:
	s_setprio 0
	v_readlane_b32 s68, v251, 44
	v_readlane_b32 s69, v251, 45
	s_mov_b64 s[4:5], s[68:69]
	s_waitcnt vmcnt(0)
	v_readlane_b32 s70, v251, 46
	v_readlane_b32 s71, v251, 47
	s_barrier
	s_and_saveexec_b64 s[0:1], s[70:71]
	v_readlane_b32 s34, v251, 37
	v_readlane_b32 s40, v251, 42
	s_xor_b64 s[2:3], exec, s[0:1]
	v_readlane_b32 s72, v251, 48
	v_readlane_b32 s30, v251, 34
	v_readlane_b32 s73, v251, 36
	v_readlane_b32 s35, v251, 38
	v_readlane_b32 s51, v251, 39
	v_readlane_b32 s36, v251, 40
	v_readlane_b32 s37, v251, 41
	s_movk_i32 s67, 0x4000
	s_mov_b32 s38, 0x800000
	s_mov_b32 s39, 0x2aaaaaab
	v_readlane_b32 s41, v251, 43
	v_readlane_b32 s31, v251, 35
	s_cbranch_execz .LBB0_1496
	v_writelane_b32 v250, s8, 44
	v_writelane_b32 v250, s9, 45
	v_writelane_b32 v250, s10, 46
	v_writelane_b32 v250, s11, 47
	v_writelane_b32 v250, s12, 48
	v_writelane_b32 v250, s13, 49
	v_writelane_b32 v250, s14, 50
	v_writelane_b32 v250, s15, 51
	s_load_dwordx2 s[8:9], s[68:69], 0xb8
	v_readfirstlane_b32 s12, v0
	v_readfirstlane_b32 s13, v1
	v_readlane_b32 s10, v250, 63
	v_readlane_b32 s11, v250, 61
	v_readlane_b32 s14, v250, 59
	v_mov_b32_e32 v0, 0
	s_mov_b32 s15, 0
	s_waitcnt lgkmcnt(0)
	s_add_u32 s8, s8, s10
	s_addc_u32 s9, s9, 0
	s_cmp_lg_u32 s11, 0
	s_cbranch_scc1 .Lgb7_known
	global_load_dword v1, v0, s[8:9] offset:128 sc1
	s_waitcnt vmcnt(0)
	v_readfirstlane_b32 s10, v1
	s_sub_u32 s11, s10, 1
	s_and_b32 s11, s11, s10
	s_cmp_eq_u32 s11, 0
	s_cselect_b32 s11, 2, 1
	s_cmp_eq_u32 s10, 0
	s_cselect_b32 s11, 1, s11
	v_writelane_b32 v250, s11, 61
	s_nop 0

.LBB0_1936:
	s_or_b64 exec, exec, s[2:3]
	s_mov_b64 s[0:1], s[68:69]
	s_waitcnt lgkmcnt(0)
	s_barrier
	s_load_dwordx2 s[2:3], s[0:1], 0xb8
	s_mov_b64 s[0:1], s[68:69]
	s_load_dwordx2 s[0:1], s[0:1], 0xb8
	s_mov_b64 s[4:5], s[68:69]
	s_load_dwordx2 s[4:5], s[4:5], 0xb8
	v_mov_b32_e32 v2, v196
	s_waitcnt lgkmcnt(0)
	s_add_u32 s0, s0, 0x1c86c000
	s_addc_u32 s1, s1, 0
	s_mov_b32 s17, 0
	s_add_u32 s14, s4, 0x1e06c000
	s_addc_u32 s15, s5, 0
	s_mov_b64 s[4:5], s[68:69]
	s_load_dwordx2 s[4:5], s[4:5], 0xb8
	s_waitcnt lgkmcnt(0)
	s_add_u32 s8, s4, 0x1f06c000
	v_and_b32_e32 v92, 48, v2
	v_lshl_add_u64 v[0:1], s[2:3], 0, v[92:93]
	s_mov_b64 s[2:3], 0x1a86c000
	v_readfirstlane_b32 s4, v2
	v_lshl_add_u64 v[160:161], v[0:1], 0, s[2:3]
	v_lshrrev_b32_e32 v0, 2, v2
	s_addc_u32 s9, s5, 0
	s_ashr_i32 s16, s4, 1
	v_and_b32_e32 v0, 12, v0
	s_andn2_b32 s16, s16, 31
	s_cmp_lt_u32 s16, 0x80
	s_cbranch_scc1 .Lprio_mla
	s_setprio 1
.Lprio_mla:
	v_and_b32_e32 v179, 15, v2
	s_mov_b32 s4, 0
	v_lshlrev_b32_e32 v162, 1, v0
	s_branch .LBB0_1938

.LBB0_2018:
	s_setprio 0
	s_mov_b64 s[4:5], s[68:69]
	s_waitcnt vmcnt(0)
	s_barrier
	s_and_saveexec_b64 s[0:1], s[70:71]
	s_xor_b64 s[2:3], exec, s[0:1]
	s_cbranch_execz .LBB0_2071
	v_writelane_b32 v250, s8, 44
	v_writelane_b32 v250, s9, 45
	v_writelane_b32 v250, s10, 46
	v_writelane_b32 v250, s11, 47
	v_writelane_b32 v250, s12, 48
	v_writelane_b32 v250, s13, 49
	v_writelane_b32 v250, s14, 50
	v_writelane_b32 v250, s15, 51
	s_load_dwordx2 s[8:9], s[68:69], 0xb8
	v_readfirstlane_b32 s12, v0
	v_readfirstlane_b32 s13, v1
	v_readlane_b32 s10, v250, 63
	v_readlane_b32 s11, v250, 61
	v_readlane_b32 s14, v250, 59
	v_mov_b32_e32 v0, 0
	s_mov_b32 s15, 0
	s_waitcnt lgkmcnt(0)
	s_add_u32 s8, s8, s10
	s_addc_u32 s9, s9, 0
	s_cmp_lg_u32 s11, 0
	s_cbranch_scc1 .Lgb12_known
	global_load_dword v1, v0, s[8:9] offset:128 sc1
	s_waitcnt vmcnt(0)
	v_readfirstlane_b32 s10, v1
	s_sub_u32 s11, s10, 1
	s_and_b32 s11, s11, s10
	s_cmp_eq_u32 s11, 0
	s_cselect_b32 s11, 2, 1
	s_cmp_eq_u32 s10, 0
	s_cselect_b32 s11, 1, s11
	v_writelane_b32 v250, s11, 61
	s_nop 0
